# gdn_out final-state combine items: each 4-element read-modify-write group issues its loads together (was 32 serial global round trips on the phase's critical path); mla_row history-row copy likewise
# speedup vs baseline: 1.0475x; 1.0090x over previous
; DI void gdn_out(CP c, int l, int item, unsigned char* sm) {
;     ...
;         for (int mt = 0; mt < 8; ++mt) { f32x4 a = (f32x4){0.f, 0.f, 0.f, 0.f};
; #pragma unroll
;             for (int s2 = 0; s2 < 4; ++s2) a = __builtin_amdgcn_mfma_f32_16x16x32_bf16(*(const bf16x8*)(As + (16 * mt + fr) * 136 + 32 * s2 + 8 * fq), Bf[s2], a, 0, 0, 0);
;             if (fin) { float* o = c->out + O_PGDN + ((size_t)l * 4 + hh) * 16384;
; #pragma unroll
;                 for (int i = 0; i < 4; ++i) o[(16 * mt + 4 * fq + i) * 128 + 16 * w + fr] += a[i]; }
.LBB0_511:
	s_lshl_b64 s[22:23], s[14:15], 16
	s_andn2_b64 vcc, exec, s[24:25]
	v_lshl_add_u32 v28, v31, 9, v28
	s_cbranch_vccnz .LBB0_513
	s_load_dwordx2 s[88:89], s[46:47], 0x128
	v_mov_b32_e32 v46, v28
	v_ashrrev_i32_e32 v47, 31, v46
	s_waitcnt lgkmcnt(0)
	s_add_u32 s88, s88, s44
	s_addc_u32 s89, s89, s45
	s_add_u32 s88, s88, s22
	s_addc_u32 s89, s89, s23
	s_add_u32 s88, s88, 0x6a27000
	s_addc_u32 s89, s89, 0
	v_lshl_add_u64 v[48:49], v[46:47], 2, s[88:89]
	global_load_dword v50, v[48:49], off
	global_load_dword v51, v[48:49], off offset:512
	global_load_dword v52, v[48:49], off offset:1024
	global_load_dword v53, v[48:49], off offset:1536
	s_waitcnt vmcnt(0)
	v_add_f32_e32 v50, v18, v50
	v_add_f32_e32 v51, v19, v51
	v_add_f32_e32 v52, v20, v52
	v_add_f32_e32 v53, v21, v53
	global_store_dword v[48:49], v50, off
	global_store_dword v[48:49], v51, off offset:512
	global_store_dword v[48:49], v52, off offset:1024
	global_store_dword v[48:49], v53, off offset:1536

; DI void gdn_out(CP c, int l, int item, unsigned char* sm) {
;     ...
;         for (int mt = 0; mt < 8; ++mt) { f32x4 a = (f32x4){0.f, 0.f, 0.f, 0.f};
; #pragma unroll
;             for (int s2 = 0; s2 < 4; ++s2) a = __builtin_amdgcn_mfma_f32_16x16x32_bf16(*(const bf16x8*)(As + (16 * mt + fr) * 136 + 32 * s2 + 8 * fq), Bf[s2], a, 0, 0, 0);
;             if (fin) { float* o = c->out + O_PGDN + ((size_t)l * 4 + hh) * 16384;
; #pragma unroll
;                 for (int i = 0; i < 4; ++i) o[(16 * mt + 4 * fq + i) * 128 + 16 * w + fr] += a[i]; }
.LBB0_515:
	s_andn2_b64 vcc, exec, s[24:25]
	s_cbranch_vccnz .LBB0_517
	s_load_dwordx2 s[88:89], s[46:47], 0x128
	v_add_u32_e32 v46, 0x800, v28
	v_ashrrev_i32_e32 v47, 31, v46
	s_waitcnt lgkmcnt(0)
	s_add_u32 s88, s88, s44
	s_addc_u32 s89, s89, s45
	s_add_u32 s88, s88, s22
	s_addc_u32 s89, s89, s23
	s_add_u32 s88, s88, 0x6a27000
	s_addc_u32 s89, s89, 0
	v_lshl_add_u64 v[48:49], v[46:47], 2, s[88:89]
	global_load_dword v50, v[48:49], off
	global_load_dword v51, v[48:49], off offset:512
	global_load_dword v52, v[48:49], off offset:1024
	global_load_dword v53, v[48:49], off offset:1536
	s_waitcnt vmcnt(0)
	v_add_f32_e32 v50, v18, v50
	v_add_f32_e32 v51, v19, v51
	v_add_f32_e32 v52, v20, v52
	v_add_f32_e32 v53, v21, v53
	global_store_dword v[48:49], v50, off
	global_store_dword v[48:49], v51, off offset:512
	global_store_dword v[48:49], v52, off offset:1024
	global_store_dword v[48:49], v53, off offset:1536

; DI void gdn_out(CP c, int l, int item, unsigned char* sm) {
;     ...
;         for (int mt = 0; mt < 8; ++mt) { f32x4 a = (f32x4){0.f, 0.f, 0.f, 0.f};
; #pragma unroll
;             for (int s2 = 0; s2 < 4; ++s2) a = __builtin_amdgcn_mfma_f32_16x16x32_bf16(*(const bf16x8*)(As + (16 * mt + fr) * 136 + 32 * s2 + 8 * fq), Bf[s2], a, 0, 0, 0);
;             if (fin) { float* o = c->out + O_PGDN + ((size_t)l * 4 + hh) * 16384;
; #pragma unroll
;                 for (int i = 0; i < 4; ++i) o[(16 * mt + 4 * fq + i) * 128 + 16 * w + fr] += a[i]; }
.LBB0_519:
	s_andn2_b64 vcc, exec, s[24:25]
	s_cbranch_vccnz .LBB0_521
	s_load_dwordx2 s[88:89], s[46:47], 0x128
	v_add_u32_e32 v46, 0x1000, v28
	v_ashrrev_i32_e32 v47, 31, v46
	s_waitcnt lgkmcnt(0)
	s_add_u32 s88, s88, s44
	s_addc_u32 s89, s89, s45
	s_add_u32 s88, s88, s22
	s_addc_u32 s89, s89, s23
	s_add_u32 s88, s88, 0x6a27000
	s_addc_u32 s89, s89, 0
	v_lshl_add_u64 v[48:49], v[46:47], 2, s[88:89]
	global_load_dword v50, v[48:49], off
	global_load_dword v51, v[48:49], off offset:512
	global_load_dword v52, v[48:49], off offset:1024
	global_load_dword v53, v[48:49], off offset:1536
	s_waitcnt vmcnt(0)
	v_add_f32_e32 v50, v18, v50
	v_add_f32_e32 v51, v19, v51
	v_add_f32_e32 v52, v20, v52
	v_add_f32_e32 v53, v21, v53
	global_store_dword v[48:49], v50, off
	global_store_dword v[48:49], v51, off offset:512
	global_store_dword v[48:49], v52, off offset:1024
	global_store_dword v[48:49], v53, off offset:1536

; DI void gdn_out(CP c, int l, int item, unsigned char* sm) {
;     ...
;         for (int mt = 0; mt < 8; ++mt) { f32x4 a = (f32x4){0.f, 0.f, 0.f, 0.f};
; #pragma unroll
;             for (int s2 = 0; s2 < 4; ++s2) a = __builtin_amdgcn_mfma_f32_16x16x32_bf16(*(const bf16x8*)(As + (16 * mt + fr) * 136 + 32 * s2 + 8 * fq), Bf[s2], a, 0, 0, 0);
;             if (fin) { float* o = c->out + O_PGDN + ((size_t)l * 4 + hh) * 16384;
; #pragma unroll
;                 for (int i = 0; i < 4; ++i) o[(16 * mt + 4 * fq + i) * 128 + 16 * w + fr] += a[i]; }
.LBB0_523:
	s_andn2_b64 vcc, exec, s[24:25]
	s_cbranch_vccnz .LBB0_525
	s_load_dwordx2 s[88:89], s[46:47], 0x128
	v_add_u32_e32 v46, 0x1800, v28
	v_ashrrev_i32_e32 v47, 31, v46
	s_waitcnt lgkmcnt(0)
	s_add_u32 s88, s88, s44
	s_addc_u32 s89, s89, s45
	s_add_u32 s88, s88, s22
	s_addc_u32 s89, s89, s23
	s_add_u32 s88, s88, 0x6a27000
	s_addc_u32 s89, s89, 0
	v_lshl_add_u64 v[48:49], v[46:47], 2, s[88:89]
	global_load_dword v50, v[48:49], off
	global_load_dword v51, v[48:49], off offset:512
	global_load_dword v52, v[48:49], off offset:1024
	global_load_dword v53, v[48:49], off offset:1536
	s_waitcnt vmcnt(0)
	v_add_f32_e32 v50, v18, v50
	v_add_f32_e32 v51, v19, v51
	v_add_f32_e32 v52, v20, v52
	v_add_f32_e32 v53, v21, v53
	global_store_dword v[48:49], v50, off
	global_store_dword v[48:49], v51, off offset:512
	global_store_dword v[48:49], v52, off offset:1024
	global_store_dword v[48:49], v53, off offset:1536

; DI void gdn_out(CP c, int l, int item, unsigned char* sm) {
;     ...
;         for (int mt = 0; mt < 8; ++mt) { f32x4 a = (f32x4){0.f, 0.f, 0.f, 0.f};
; #pragma unroll
;             for (int s2 = 0; s2 < 4; ++s2) a = __builtin_amdgcn_mfma_f32_16x16x32_bf16(*(const bf16x8*)(As + (16 * mt + fr) * 136 + 32 * s2 + 8 * fq), Bf[s2], a, 0, 0, 0);
;             if (fin) { float* o = c->out + O_PGDN + ((size_t)l * 4 + hh) * 16384;
; #pragma unroll
;                 for (int i = 0; i < 4; ++i) o[(16 * mt + 4 * fq + i) * 128 + 16 * w + fr] += a[i]; }
.LBB0_527:
	s_andn2_b64 vcc, exec, s[24:25]
	s_cbranch_vccnz .LBB0_529
	s_load_dwordx2 s[88:89], s[46:47], 0x128
	v_add_u32_e32 v46, 0x2000, v28
	v_ashrrev_i32_e32 v47, 31, v46
	s_waitcnt lgkmcnt(0)
	s_add_u32 s88, s88, s44
	s_addc_u32 s89, s89, s45
	s_add_u32 s88, s88, s22
	s_addc_u32 s89, s89, s23
	s_add_u32 s88, s88, 0x6a27000
	s_addc_u32 s89, s89, 0
	v_lshl_add_u64 v[48:49], v[46:47], 2, s[88:89]
	global_load_dword v50, v[48:49], off
	global_load_dword v51, v[48:49], off offset:512
	global_load_dword v52, v[48:49], off offset:1024
	global_load_dword v53, v[48:49], off offset:1536
	s_waitcnt vmcnt(0)
	v_add_f32_e32 v50, v18, v50
	v_add_f32_e32 v51, v19, v51
	v_add_f32_e32 v52, v20, v52
	v_add_f32_e32 v53, v21, v53
	global_store_dword v[48:49], v50, off
	global_store_dword v[48:49], v51, off offset:512
	global_store_dword v[48:49], v52, off offset:1024
	global_store_dword v[48:49], v53, off offset:1536

; DI void gdn_out(CP c, int l, int item, unsigned char* sm) {
;     ...
;         for (int mt = 0; mt < 8; ++mt) { f32x4 a = (f32x4){0.f, 0.f, 0.f, 0.f};
; #pragma unroll
;             for (int s2 = 0; s2 < 4; ++s2) a = __builtin_amdgcn_mfma_f32_16x16x32_bf16(*(const bf16x8*)(As + (16 * mt + fr) * 136 + 32 * s2 + 8 * fq), Bf[s2], a, 0, 0, 0);
;             if (fin) { float* o = c->out + O_PGDN + ((size_t)l * 4 + hh) * 16384;
; #pragma unroll
;                 for (int i = 0; i < 4; ++i) o[(16 * mt + 4 * fq + i) * 128 + 16 * w + fr] += a[i]; }
.LBB0_531:
	s_andn2_b64 vcc, exec, s[24:25]
	s_cbranch_vccnz .LBB0_533
	s_load_dwordx2 s[88:89], s[46:47], 0x128
	v_add_u32_e32 v46, 0x2800, v28
	v_ashrrev_i32_e32 v47, 31, v46
	s_waitcnt lgkmcnt(0)
	s_add_u32 s88, s88, s44
	s_addc_u32 s89, s89, s45
	s_add_u32 s88, s88, s22
	s_addc_u32 s89, s89, s23
	s_add_u32 s88, s88, 0x6a27000
	s_addc_u32 s89, s89, 0
	v_lshl_add_u64 v[48:49], v[46:47], 2, s[88:89]
	global_load_dword v50, v[48:49], off
	global_load_dword v51, v[48:49], off offset:512
	global_load_dword v52, v[48:49], off offset:1024
	global_load_dword v53, v[48:49], off offset:1536
	s_waitcnt vmcnt(0)
	v_add_f32_e32 v50, v18, v50
	v_add_f32_e32 v51, v19, v51
	v_add_f32_e32 v52, v20, v52
	v_add_f32_e32 v53, v21, v53
	global_store_dword v[48:49], v50, off
	global_store_dword v[48:49], v51, off offset:512
	global_store_dword v[48:49], v52, off offset:1024
	global_store_dword v[48:49], v53, off offset:1536

; DI void gdn_out(CP c, int l, int item, unsigned char* sm) {
;     ...
;         for (int mt = 0; mt < 8; ++mt) { f32x4 a = (f32x4){0.f, 0.f, 0.f, 0.f};
; #pragma unroll
;             for (int s2 = 0; s2 < 4; ++s2) a = __builtin_amdgcn_mfma_f32_16x16x32_bf16(*(const bf16x8*)(As + (16 * mt + fr) * 136 + 32 * s2 + 8 * fq), Bf[s2], a, 0, 0, 0);
;             if (fin) { float* o = c->out + O_PGDN + ((size_t)l * 4 + hh) * 16384;
; #pragma unroll
;                 for (int i = 0; i < 4; ++i) o[(16 * mt + 4 * fq + i) * 128 + 16 * w + fr] += a[i]; }
.LBB0_535:
	s_andn2_b64 vcc, exec, s[24:25]
	s_cbranch_vccnz .LBB0_537
	s_load_dwordx2 s[88:89], s[46:47], 0x128
	v_add_u32_e32 v46, 0x3000, v28
	v_ashrrev_i32_e32 v47, 31, v46
	s_waitcnt lgkmcnt(0)
	s_add_u32 s88, s88, s44
	s_addc_u32 s89, s89, s45
	s_add_u32 s88, s88, s22
	s_addc_u32 s89, s89, s23
	s_add_u32 s88, s88, 0x6a27000
	s_addc_u32 s89, s89, 0
	v_lshl_add_u64 v[48:49], v[46:47], 2, s[88:89]
	global_load_dword v50, v[48:49], off
	global_load_dword v51, v[48:49], off offset:512
	global_load_dword v52, v[48:49], off offset:1024
	global_load_dword v53, v[48:49], off offset:1536
	s_waitcnt vmcnt(0)
	v_add_f32_e32 v50, v18, v50
	v_add_f32_e32 v51, v19, v51
	v_add_f32_e32 v52, v20, v52
	v_add_f32_e32 v53, v21, v53
	global_store_dword v[48:49], v50, off
	global_store_dword v[48:49], v51, off offset:512
	global_store_dword v[48:49], v52, off offset:1024
	global_store_dword v[48:49], v53, off offset:1536

; DI void gdn_out(CP c, int l, int item, unsigned char* sm) {
;     ...
;         for (int mt = 0; mt < 8; ++mt) { f32x4 a = (f32x4){0.f, 0.f, 0.f, 0.f};
; #pragma unroll
;             for (int s2 = 0; s2 < 4; ++s2) a = __builtin_amdgcn_mfma_f32_16x16x32_bf16(*(const bf16x8*)(As + (16 * mt + fr) * 136 + 32 * s2 + 8 * fq), Bf[s2], a, 0, 0, 0);
;             if (fin) { float* o = c->out + O_PGDN + ((size_t)l * 4 + hh) * 16384;
; #pragma unroll
;                 for (int i = 0; i < 4; ++i) o[(16 * mt + 4 * fq + i) * 128 + 16 * w + fr] += a[i]; }
.LBB0_539:
	s_andn2_b64 vcc, exec, s[24:25]
	s_cbranch_vccnz .LBB0_541
	s_load_dwordx2 s[88:89], s[46:47], 0x128
	v_add_u32_e32 v46, 0x3800, v28
	v_ashrrev_i32_e32 v47, 31, v46
	s_waitcnt lgkmcnt(0)
	s_add_u32 s88, s88, s44
	s_addc_u32 s89, s89, s45
	s_add_u32 s88, s88, s22
	s_addc_u32 s89, s89, s23
	s_add_u32 s88, s88, 0x6a27000
	s_addc_u32 s89, s89, 0
	v_lshl_add_u64 v[48:49], v[46:47], 2, s[88:89]
	global_load_dword v50, v[48:49], off
	global_load_dword v51, v[48:49], off offset:512
	global_load_dword v52, v[48:49], off offset:1024
	global_load_dword v53, v[48:49], off offset:1536
	s_waitcnt vmcnt(0)
	v_add_f32_e32 v50, v2, v50
	v_add_f32_e32 v51, v3, v51
	v_add_f32_e32 v52, v4, v52
	v_add_f32_e32 v53, v5, v53
	global_store_dword v[48:49], v50, off
	global_store_dword v[48:49], v51, off offset:512
	global_store_dword v[48:49], v52, off offset:1024
	global_store_dword v[48:49], v53, off offset:1536

; DI void gdn_chunk(CP c, int l, int item, float* sm) {
;     ...
; #pragma unroll
;             for (int r = 1; r < 8; ++r)
; #pragma unroll
;                 for (int r2 = 0; r2 < r; ++r2) acc[r] -= Ls[(i0 + r2) * 68 + i0 + r] * acc[r2];
; #pragma unroll
;             for (int r = 0; r < 8; ++r) R[(i0 + r) * 260 + col] = acc[r];
.LBB0_958:
	s_lshl_b32 s0, s7, 2
	s_mul_i32 s1, s7, 0x110
	s_add_i32 s0, s0, s1
	s_add_i32 s0, s0, 0x20c00
	v_mov_b32_e32 v26, s0
	ds_read_b128 v[42:45], v26
	ds_read_b128 v[46:49], v26 offset:16
	ds_read_b128 v[50:53], v26 offset:272
	ds_read_b128 v[54:57], v26 offset:288
	ds_read_b128 v[58:61], v26 offset:544
	ds_read_b128 v[74:77], v26 offset:560
	ds_read_b128 v[84:87], v26 offset:816
	ds_read_b128 v[88:91], v26 offset:832
	ds_read_b128 v[124:127], v26 offset:1088
	ds_read_b128 v[128:131], v26 offset:1104
	ds_read_b128 v[132:135], v26 offset:1360
	ds_read_b128 v[136:139], v26 offset:1376
	ds_read_b128 v[140:143], v26 offset:1632
	ds_read_b128 v[144:147], v26 offset:1648
	s_add_i32 s7, s7, 8
	s_add_i32 s6, s6, 32
	s_cmp_ge_u32 s7, s93
	s_waitcnt lgkmcnt(12)
	v_fma_f32 v3, -v2, v43, v3
	v_fma_f32 v8, -v2, v44, v8
	v_fma_f32 v9, -v2, v45, v9
	v_fma_f32 v6, -v2, v46, v6
	v_fma_f32 v7, -v2, v47, v7
	v_fma_f32 v4, -v2, v48, v4
	v_fma_f32 v5, -v2, v49, v5
	s_waitcnt lgkmcnt(10)
	v_fma_f32 v8, -v3, v52, v8
	v_fma_f32 v9, -v3, v53, v9
	v_fma_f32 v6, -v3, v54, v6
	v_fma_f32 v7, -v3, v55, v7
	v_fma_f32 v4, -v3, v56, v4
	v_fma_f32 v5, -v3, v57, v5
	s_waitcnt lgkmcnt(8)
	v_fma_f32 v9, -v8, v61, v9
	v_fma_f32 v6, -v8, v74, v6
	v_fma_f32 v7, -v8, v75, v7
	v_fma_f32 v4, -v8, v76, v4
	v_fma_f32 v5, -v8, v77, v5
	s_waitcnt lgkmcnt(6)
	v_fma_f32 v6, -v9, v88, v6
	v_fma_f32 v7, -v9, v89, v7
	v_fma_f32 v4, -v9, v90, v4
	v_fma_f32 v5, -v9, v91, v5
	s_waitcnt lgkmcnt(4)
	v_fma_f32 v7, -v6, v129, v7
	v_fma_f32 v4, -v6, v130, v4
	v_fma_f32 v5, -v6, v131, v5
	s_waitcnt lgkmcnt(2)
	v_fma_f32 v4, -v7, v138, v4
	v_fma_f32 v5, -v7, v139, v5
	s_waitcnt lgkmcnt(0)
	v_fma_f32 v5, -v4, v147, v5
	ds_write_b32 v11, v2
	ds_write_b32 v11, v3 offset:1040
	ds_write_b32 v11, v8 offset:2080
	ds_write_b32 v11, v9 offset:3120
	ds_write_b32 v11, v6 offset:4160
	ds_write_b32 v11, v7 offset:5200
	ds_write_b32 v11, v4 offset:6240
	ds_write_b32 v11, v5 offset:7280
	s_cbranch_scc1 .LBB0_961

; DI float bf2f(bf16_t b) { return __uint_as_float(((unsigned)b) << 16); }
; DI void mla_row(CP c, int l, int r, int lane) {
;     ...
;     float* gco = nullptr;
;     if (!samp && r >= MP - 3) gco = c->out + O_PGC + ((size_t)l * 3 + (r - (MP - 3))) * 1536;
;     if (samp && t >= 13) gco = c->out + O_SGC + ((size_t)(l * 32 + b) * 3 + (t - 13)) * 1536;
;     if (gco) for (int i = 0; i < 24; ++i) gco[lane + 64 * i] = bf2f(z[1024 + lane + 64 * i]);
.LBB0_1074:
	s_or_b64 exec, exec, s[18:19]
	v_cmp_ne_u64_e32 vcc, 0, v[2:3]
	s_and_saveexec_b64 s[18:19], vcc
	s_cbranch_execz .LBB0_1051
	v_lshl_add_u64 v[6:7], s[20:21], 0, v[30:31]
	v_add_co_u32_e32 v8, vcc, 0x2e54000, v6
	s_mov_b32 s14, 0x2e55000
	s_nop 0
	v_addc_co_u32_e32 v9, vcc, 0, v7, vcc
	v_add_co_u32_e32 v6, vcc, s14, v6
	v_mov_b32_e32 v35, v1
	s_nop 0
	v_addc_co_u32_e32 v7, vcc, 0, v7, vcc
	s_movk_i32 s14, 0x1000
	v_lshlrev_b32_e32 v0, 2, v12
	v_lshl_add_u64 v[4:5], v[2:3], 0, v[0:1]
	v_lshl_add_u64 v[2:3], v[2:3], 0, v[34:35]
	v_add_co_u32_e32 v2, vcc, s14, v4
	v_addc_co_u32_e32 v3, vcc, 0, v5, vcc
	global_load_ushort v124, v[8:9], off offset:2048
	global_load_ushort v125, v[8:9], off offset:2176
	global_load_ushort v126, v[8:9], off offset:2304
	global_load_ushort v127, v[8:9], off offset:2432
	global_load_ushort v128, v[8:9], off offset:2560
	global_load_ushort v129, v[8:9], off offset:2688
	global_load_ushort v130, v[8:9], off offset:2816
	global_load_ushort v131, v[8:9], off offset:2944
	global_load_ushort v132, v[8:9], off offset:3072
	global_load_ushort v133, v[8:9], off offset:3200
	global_load_ushort v134, v[8:9], off offset:3328
	global_load_ushort v135, v[8:9], off offset:3456
	global_load_ushort v136, v[8:9], off offset:3584
	global_load_ushort v137, v[8:9], off offset:3712
	global_load_ushort v138, v[8:9], off offset:3840
	global_load_ushort v139, v[8:9], off offset:3968
	global_load_ushort v140, v[6:7], off
	global_load_ushort v141, v[6:7], off offset:128
	global_load_ushort v142, v[6:7], off offset:256
	global_load_ushort v143, v[6:7], off offset:384
	global_load_ushort v144, v[6:7], off offset:512
	global_load_ushort v145, v[6:7], off offset:640
	global_load_ushort v146, v[6:7], off offset:768
	global_load_ushort v147, v[6:7], off offset:896
	s_waitcnt vmcnt(0)
	v_lshlrev_b32_e32 v124, 16, v124
	global_store_dword v[4:5], v124, off
	v_lshlrev_b32_e32 v125, 16, v125
	global_store_dword v[4:5], v125, off offset:256
	v_lshlrev_b32_e32 v126, 16, v126
	global_store_dword v[4:5], v126, off offset:512
	v_lshlrev_b32_e32 v127, 16, v127
	global_store_dword v[4:5], v127, off offset:768
	v_lshlrev_b32_e32 v128, 16, v128
	global_store_dword v[4:5], v128, off offset:1024
	v_lshlrev_b32_e32 v129, 16, v129
	global_store_dword v[4:5], v129, off offset:1280
	v_lshlrev_b32_e32 v130, 16, v130
	global_store_dword v[4:5], v130, off offset:1536
	v_lshlrev_b32_e32 v131, 16, v131
	global_store_dword v[4:5], v131, off offset:1792
	v_lshlrev_b32_e32 v132, 16, v132
	global_store_dword v[4:5], v132, off offset:2048
	v_lshlrev_b32_e32 v133, 16, v133
	global_store_dword v[4:5], v133, off offset:2304
	v_lshlrev_b32_e32 v134, 16, v134
	global_store_dword v[4:5], v134, off offset:2560
	v_lshlrev_b32_e32 v135, 16, v135
	global_store_dword v[4:5], v135, off offset:2816
	v_lshlrev_b32_e32 v136, 16, v136
	global_store_dword v[4:5], v136, off offset:3072
	v_lshlrev_b32_e32 v137, 16, v137
	global_store_dword v[4:5], v137, off offset:3328
	v_lshlrev_b32_e32 v138, 16, v138
	global_store_dword v[4:5], v138, off offset:3584
	v_lshlrev_b32_e32 v139, 16, v139
	global_store_dword v[4:5], v139, off offset:3840
	v_lshlrev_b32_e32 v140, 16, v140
	global_store_dword v[2:3], v140, off
	v_lshlrev_b32_e32 v141, 16, v141
	global_store_dword v[2:3], v141, off offset:256
	v_lshlrev_b32_e32 v142, 16, v142
	global_store_dword v[2:3], v142, off offset:512
	v_lshlrev_b32_e32 v143, 16, v143
	global_store_dword v[2:3], v143, off offset:768
	v_lshlrev_b32_e32 v144, 16, v144
	global_store_dword v[2:3], v144, off offset:1024
	v_lshlrev_b32_e32 v145, 16, v145
	global_store_dword v[2:3], v145, off offset:1280
	v_lshlrev_b32_e32 v146, 16, v146
	global_store_dword v[2:3], v146, off offset:1536
	v_lshlrev_b32_e32 v147, 16, v147
	global_store_dword v[2:3], v147, off offset:1792
	s_branch .LBB0_1051
